# final RMSNorm: gain loads hoisted, dwordx4 loads, next-row prefetch; grid barrier exit: redundant L2 writeback removed
# speedup vs baseline: 1.0196x; 1.0054x over previous
; __device__ __forceinline__ void run_phase(int ph, KParams kp, unsigned char* smem) {
;     ...
;     case 2: {
;       for (int it = blockIdx.x; it < 2048 + 6144; it += gridDim.x) {
;         if (it < 2048) {
;           int seqbase, qi, h, nt;
;           if (gridDim.x == 512) {
;             const int bid = blockIdx.x, i = it >> 9, xcd = bid & 7, l = (bid >> 3) + 64 * (i & 1);
;             if (it < 1024) { const int g = xcd >> 1, id = l * 2 + (xcd & 1); qi = id >> 2; h = (g & 1) * 4 + (id & 3); seqbase = NPROMPT + (g >> 1) * 16384; nt = 256; }
;             else { const int grp = xcd + 8 * (l >> 5), id = l & 31; qi = id >> 2; h = (grp & 1) * 4 + (id & 3); seqbase = (grp >> 1) * 2048; nt = 32; }
;           } else if (it < 1024) { const int s = it >> 9, rem = it & 511; qi = rem >> 3; h = rem & 7; seqbase = NPROMPT + s * 16384; nt = 256; }
;           else { const int a = it - 1024; const int s = a >> 6, rem = a & 63; qi = rem >> 3; h = rem & 7; seqbase = s * 2048; nt = 32; }
;           CtxA c{Z + (size_t)(seqbase + 256 * qi) * ZW + h * 64, Z + (size_t)seqbase * ZW + 512 + (h >> 2) * 64, nt};
;     ...
;     while (__hip_atomic_load(st + 32 * 9, __ATOMIC_RELAXED, __HIP_MEMORY_SCOPE_AGENT) == gen) __builtin_amdgcn_s_sleep(1);
;     __threadfence();
;   }
;   __syncthreads();
.LBB0_170:
	s_sleep 1
	global_load_dword v2, v1, s[4:5] sc1
	s_waitcnt vmcnt(0)
	v_cmp_eq_u32_e32 vcc, v2, v0
	s_cbranch_vccnz .LBB0_170
.LBB0_171:
	buffer_inv sc1
.LBB0_172:
	s_or_b64 exec, exec, s[0:1]
	s_mov_b64 s[0:1], s[26:27]
	s_barrier
	s_load_dwordx2 s[42:43], s[0:1], 0xb0
	v_readlane_b32 s0, v248, 3
	v_mov_b32_e32 v0, v210
	s_cmpk_gt_i32 s0, 0x1fff
	s_cbranch_scc1 .LBB0_224
	s_waitcnt lgkmcnt(0)
	s_add_u32 s86, s42, 0x6788000
	s_addc_u32 s87, s43, 0
	v_writelane_b32 v248, s84, 6
	s_add_u32 s0, s42, 0x6480000
	v_writelane_b32 v248, s0, 8
	s_addc_u32 s0, s43, 0
	v_writelane_b32 v248, s0, 9
	v_mbcnt_hi_u32_b32 v214, -1, v211
	v_readlane_b32 s2, v248, 3
	s_and_b32 s0, s2, 7
	s_ashr_i32 s1, s2, 3
	v_writelane_b32 v248, s0, 10
	s_bfe_u32 s0, s1, 0x30002
	v_writelane_b32 v248, s0, 12
	s_lshl_b32 s0, s2, 2
	s_and_b32 s0, s0, 4
	v_writelane_b32 v248, s1, 13
	s_and_b32 s1, s1, 3
	s_or_b32 s0, s0, s1
	s_lshl_b32 s1, s2, 1
	v_writelane_b32 v248, s0, 14
	s_and_b32 s0, s2, 1
	s_and_b32 s1, s1, 4
	s_or_b32 s0, s1, s0
	v_writelane_b32 v248, s0, 15
	s_lshl_b32 s0, s2, 12
	s_and_b32 s0, s0, 0x4000
	v_and_b32_e32 v0, 64, v214
	s_bitset1_b32 s0, 15
	s_mov_b32 s45, 0
	s_movk_i32 s97, 0x1800
	v_mov_b32_e32 v189, 0
	s_mov_b64 s[46:47], 0x600
	s_movk_i32 s60, 0x90
	s_mov_b32 s90, 0xf149f2ca
	s_movk_i32 s94, 0x41
	s_mov_b32 s95, 0x3e38aa3b
	s_mov_b64 s[52:53], 0x67e8400
	s_mov_b64 s[54:55], 0x67e8500
	v_mov_b32_e32 v212, 0x42800000
	v_mov_b32_e32 v213, 0x41800000
	v_mov_b32_e32 v190, 0xf149f2ca
	v_xor_b32_e32 v215, 16, v214
	v_add_u32_e32 v216, 64, v0
	v_xor_b32_e32 v217, 32, v214
	v_mov_b32_e32 v192, 0x3e38aa3b
	v_writelane_b32 v248, s0, 16
	s_branch .LBB0_176

; __device__ __forceinline__ void run_phase(int ph, KParams kp, unsigned char* smem) {
;     ...
;     case 3: {
;       const float* lse = (const float*)(ws + WS_LSE);
;       for (int i = blockIdx.x * 256 + tid; i < NTOK * 32; i += gridDim.x * 256) {
;         const int T = i >> 5, h = (i >> 3) & 3, c8 = i & 7;
;         int sb, pos, lg;
;         if (T < NPROMPT) { sb = T & ~2047; pos = T & 2047; lg = 11; } else { sb = NPROMPT + ((T - NPROMPT) & ~16383); pos = (T - NPROMPT) & 16383; lg = 14; }
;     ...
;     while (__hip_atomic_load(st + 32 * 9, __ATOMIC_RELAXED, __HIP_MEMORY_SCOPE_AGENT) == gen) __builtin_amdgcn_s_sleep(1);
;     __threadfence();
;   }
;   __syncthreads();
.LBB0_234:
	s_sleep 1
	global_load_dword v2, v1, s[4:5] sc1
	s_waitcnt vmcnt(0)
	v_cmp_eq_u32_e32 vcc, v2, v0
	s_cbranch_vccnz .LBB0_234
.LBB0_235:
	buffer_inv sc1
.LBB0_236:
	s_or_b64 exec, exec, s[0:1]
	s_mov_b64 s[0:1], s[26:27]
	s_barrier
	s_load_dwordx2 s[0:1], s[0:1], 0xb0
	v_mov_b32_e32 v0, v210
	s_mov_b32 s2, 0x200000
	v_add_u32_e32 v4, s84, v0
	v_cmp_gt_i32_e32 vcc, s2, v4
	s_and_saveexec_b64 s[6:7], vcc
	s_cbranch_execz .LBB0_239
	s_waitcnt lgkmcnt(0)
	s_add_u32 s4, s0, 0x6788000
	s_addc_u32 s5, s1, 0
	s_add_u32 s8, s0, 0x6480000
	v_readlane_b32 s3, v248, 0
	v_lshlrev_b32_e32 v0, 3, v0
	v_readlane_b32 s10, v248, 3
	s_addc_u32 s9, s1, 0
	s_lshl_b32 s2, s3, 8
	v_lshl_add_u32 v5, s10, 11, v0
	s_lshl_b32 s12, s3, 11
	s_mov_b64 s[10:11], 0
	s_mov_b32 s13, 0x8000
	v_mov_b32_e32 v6, 0x3fff
	v_mov_b32_e32 v7, 0x7ff
	v_mov_b32_e32 v8, 0x7fffc000
	v_mov_b32_e32 v9, 0xfffff800
	v_mov_b32_e32 v1, 0
	s_movk_i32 s14, 0x3ffc
	s_movk_i32 s15, 0x1800
	v_mov_b64_e32 v[2:3], s[4:5]
	s_mov_b32 s16, 0x1fffff

; __device__ __forceinline__ void run_phase(int ph, KParams kp, unsigned char* smem) {
;     ...
;     case 4: case 7: case 9: case 12: case 15: case 17: {
;       const bf16_t* A; int lda, K; const bf16_t* Bt;
;       if (ph == 4) { A = Z; lda = ZW; K = 768; Bt = (const bf16_t*)(ws + WS_WT_OUT_AB); }
;       else if (ph == 12) { A = Z; lda = ZW; K = 1024; Bt = (const bf16_t*)(ws + WS_WT_OUT_C); }
;       else if (ph == 7 || ph == 15) { A = Z; lda = 1024; K = 1024; Bt = (const bf16_t*)(ws + WS_WT_O) + (size_t)L * 1024 * 1024; }
;       else { A = Z; lda = DFF; K = DFF; Bt = (const bf16_t*)(ws + WS_WT_DOWN) + (size_t)L * 1024 * DFF; }
;       GPre pr; bool pre = false;
;       for (int t = blockIdx.x; t < 512 * 4; t += gridDim.x) {
;         int mt, nt; tile_map(t, 4, gridDim.x, mt, nt);
;         const bool hn = t + (int)gridDim.x < 512 * 4; int mtn = 0, ntn = 0; if (hn) tile_map(t + gridDim.x, 4, gridDim.x, mtn, ntn);
;         EpiResid e{ph == 4 ? xin_row(kp->x_prompt, kp->x_sample, mt * 128) : kp->out + (size_t)mt * 128 * 1024, kp->out};
;         gemm_tile<false>(smem, A + (size_t)mt * 128 * lda, lda, Bt, 1024, K, e, mt * 128, nt * 256, pr, pre, A + (size_t)mtn * 128 * lda, ntn * 256, hn); pre = hn;
;     ...
;     while (__hip_atomic_load(st + 32 * 9, __ATOMIC_RELAXED, __HIP_MEMORY_SCOPE_AGENT) == gen) __builtin_amdgcn_s_sleep(1);
;     __threadfence();
;   }
;   __syncthreads();
.LBB0_249:
	s_sleep 1
	global_load_dword v2, v1, s[6:7] sc1
	s_waitcnt vmcnt(0)
	v_cmp_eq_u32_e32 vcc, v2, v0
	s_cbranch_vccnz .LBB0_249
.LBB0_250:
	buffer_inv sc1
.LBB0_251:
	s_or_b64 exec, exec, s[4:5]
	s_mov_b64 s[14:15], s[26:27]
	s_barrier
	s_load_dwordx2 s[0:1], s[14:15], 0xb0
	v_readlane_b32 s2, v248, 3
	s_cmpk_lt_i32 s2, 0x800
	v_mov_b32_e32 v0, v210
	s_cselect_b64 s[8:9], -1, 0
	s_cmpk_gt_i32 s2, 0x7ff
	s_cbranch_scc1 .LBB0_270
	s_waitcnt lgkmcnt(0)
	s_add_u32 s2, s0, 0x6788000
	s_addc_u32 s33, s1, 0
	s_add_u32 s58, s0, 0x600000
	v_readlane_b32 s16, v248, 0
	s_addc_u32 s59, s1, 0
	s_and_b32 s3, s16, 7
	s_cmp_lg_u32 s3, 0
	s_cselect_b64 s[10:11], -1, 0
	s_abs_i32 s60, s16
	v_cvt_f32_u32_e32 v0, s60
	s_load_dwordx2 s[12:13], s[14:15], 0xa8
	s_load_dwordx4 s[4:7], s[14:15], 0x0
	s_sub_i32 s3, 0, s60
	s_ashr_i32 s62, s16, 3
	v_rcp_iflag_f32_e32 v0, v0
	s_ashr_i32 s63, s16, 31
	s_mov_b64 s[52:53], 0
	s_movk_i32 s61, 0xc00
	v_mul_f32_e32 v0, 0x4f7ffffe, v0
	v_cvt_u32_f32_e32 v0, v0
	v_mov_b32_e32 v153, 0
	s_mov_b64 s[16:17], 0x60000
	s_mov_b64 s[18:19], 0x1000
	v_readfirstlane_b32 s14, v0
	s_mul_i32 s3, s3, s14
	s_mul_hi_u32 s3, s14, s3
	s_add_i32 s64, s14, s3
	s_add_u32 s65, s0, 0x620000
	s_addc_u32 s66, s1, 0
	s_add_u32 s14, s0, 0x6788080
	s_addc_u32 s15, s1, 0
	s_mov_b64 s[20:21], 0x2000
	s_mov_b64 s[22:23], 0x3000
	s_mov_b64 s[24:25], 0x60040
	s_mov_b64 s[26:27], 0x10000
	s_mov_b64 s[28:29], 0x11000
	s_mov_b64 s[30:31], 0x12000
	s_mov_b64 s[34:35], 0x13000
	s_movk_i32 s67, 0x50
	s_movk_i32 s68, 0x1800
	s_mov_b64 s[36:37], 0x80
	s_mov_b64 s[38:39], 0xc0
	s_mov_b64 s[40:41], 0x100
	s_mov_b64 s[42:43], 0x140
	s_mov_b64 s[44:45], 0x180
	s_mov_b64 s[46:47], 0x1c0
	v_readlane_b32 s56, v248, 3
	s_waitcnt vmcnt(0)
	s_branch .LBB0_254

; __device__ __forceinline__ void run_phase(int ph, KParams kp, unsigned char* smem) {
;     ...
;     case 5: case 10: case 13: {
;       const bf16_t* Bt; int NT, ldc;
;       if (ph == 10) { Bt = (const bf16_t*)(ws + WS_WT_IN_C); NT = 12; ldc = ZW; }
;       else { Bt = (const bf16_t*)(ws + WS_WT_Q) + (size_t)L * 1024 * 1024; NT = 4; ldc = 1024; }
;       GPre pr; bool pre = false;
;       for (int t = blockIdx.x; t < 512 * NT; t += gridDim.x) {
;         int mt, nt; tile_map(t, NT, gridDim.x, mt, nt);
;         const bool hn = t + (int)gridDim.x < 512 * NT; int mtn = 0, ntn = 0; if (hn) tile_map(t + gridDim.x, NT, gridDim.x, mtn, ntn);
;         EpiStore<true> e{Z, ldc};
;         gemm_tile<true>(smem, kp->out + (size_t)mt * 128 * 1024, 1024, Bt, NT * 256, 1024, e, mt * 128, nt * 256, pr, pre, kp->out + (size_t)mtn * 128 * 1024, ntn * 256, hn); pre = hn;
;     ...
;     while (__hip_atomic_load(st + 32 * 9, __ATOMIC_RELAXED, __HIP_MEMORY_SCOPE_AGENT) == gen) __builtin_amdgcn_s_sleep(1);
;     __threadfence();
;   }
;   __syncthreads();
.LBB0_280:
	s_sleep 1
	global_load_dword v2, v1, s[6:7] sc1
	s_waitcnt vmcnt(0)
	v_cmp_eq_u32_e32 vcc, v2, v0
	s_cbranch_vccnz .LBB0_280
.LBB0_281:
	buffer_inv sc1
.LBB0_282:
	s_or_b64 exec, exec, s[4:5]
	s_mov_b64 s[6:7], s[26:27]
	s_barrier
	s_load_dwordx2 s[0:1], s[6:7], 0xb0
	v_cndmask_b32_e64 v1, 0, 1, s[8:9]
	v_cmp_ne_u32_e64 s[2:3], 1, v1
	v_mov_b32_e32 v0, v210
	s_andn2_b64 vcc, exec, s[8:9]
	v_writelane_b32 v248, s2, 17
	s_nop 1
	v_writelane_b32 v248, s3, 18
	s_cbranch_vccnz .LBB0_310
	s_waitcnt lgkmcnt(0)
	s_add_u32 s4, s0, 0x6788000
	s_addc_u32 s5, s1, 0
	s_add_u32 s2, s0, 0xf80000
	v_readlane_b32 s12, v248, 0
	s_addc_u32 s33, s1, 0
	s_and_b32 s3, s12, 7
	s_cmp_lg_u32 s3, 0
	s_cselect_b64 s[8:9], -1, 0
	s_abs_i32 s56, s12
	v_cvt_f32_u32_e32 v0, s56
	s_load_dwordx2 s[10:11], s[6:7], 0xa8
	s_sub_i32 s3, 0, s56
	s_ashr_i32 s57, s12, 3
	v_rcp_iflag_f32_e32 v0, v0
	s_ashr_i32 s58, s12, 31
	s_mov_b64 s[48:49], 0
	v_mov_b32_e32 v177, 0
	v_mul_f32_e32 v0, 0x4f7ffffe, v0
	v_cvt_u32_f32_e32 v0, v0
	s_mov_b64 s[14:15], 0x20000
	s_mov_b64 s[16:17], 0x40000
	s_mov_b64 s[18:19], 0x60000
	v_readfirstlane_b32 s6, v0
	s_mul_i32 s3, s3, s6
	s_mul_hi_u32 s3, s6, s3
	s_add_i32 s59, s6, s3
	s_add_u32 s60, s0, 0xfa0000
	s_addc_u32 s61, s1, 0
	s_waitcnt lgkmcnt(0)
	s_add_u32 s12, s10, 0x100
	s_addc_u32 s13, s11, 0
	s_mov_b64 s[20:21], 0x1000
	s_mov_b64 s[22:23], 0x2000
	s_mov_b64 s[24:25], 0x3000
	s_mov_b64 s[26:27], 0x80
	s_mov_b64 s[28:29], 0x20080
	s_mov_b64 s[30:31], 0x40080
	s_mov_b64 s[34:35], 0x60080
	s_mov_b64 s[36:37], 0x10000
	s_mov_b64 s[38:39], 0x11000
	s_mov_b64 s[40:41], 0x12000
	s_mov_b64 s[42:43], 0x13000
	s_movk_i32 s62, 0x50
	v_mbcnt_hi_u32_b32 v191, -1, v211
	v_mov_b32_e32 v192, 0x358637bd
	s_mov_b32 s63, 0x800000
	v_readlane_b32 s47, v248, 3
	s_waitcnt vmcnt(0)
	s_branch .LBB0_285

; __device__ __forceinline__ void run_phase(int ph, KParams kp, unsigned char* smem) {
;     ...
;     case 6: case 14: {
;       const bf16_t* kvm = (const bf16_t*)(ws + WS_KVMEM) + (size_t)L * 4608 * 2048;
;       for (int it = blockIdx.x; it < 4096; it += gridDim.x) {
;         int idx = it; if (gridDim.x == 512) idx = (blockIdx.x & 7) * 512 + (blockIdx.x >> 3) + 64 * (it >> 9);
;         const int h = idx & 3, tile = idx >> 2, T0 = tile * 64;
;         const int bidx = T0 < NPROMPT ? (T0 >> 11) : 16 + ((T0 - NPROMPT) >> 14);
;         CtxX c{Z + (size_t)T0 * 1024 + h * 256, kvm + (size_t)bidx * 256 * 2048 + h * 256};
;     ...
;     while (__hip_atomic_load(st + 32 * 9, __ATOMIC_RELAXED, __HIP_MEMORY_SCOPE_AGENT) == gen) __builtin_amdgcn_s_sleep(1);
;     __threadfence();
;   }
;   __syncthreads();
.LBB0_320:
	s_sleep 1
	global_load_dword v2, v1, s[6:7] sc1
	s_waitcnt vmcnt(0)
	v_cmp_eq_u32_e32 vcc, v2, v0
	s_cbranch_vccnz .LBB0_320
.LBB0_321:
	buffer_inv sc1
.LBB0_322:
	s_or_b64 exec, exec, s[4:5]
	s_mov_b64 s[0:1], s[26:27]
	s_barrier
	s_load_dwordx2 s[0:1], s[0:1], 0xb0
	v_readlane_b32 s2, v248, 3
	s_cmpk_lt_i32 s2, 0x1000
	v_mov_b32_e32 v0, v210
	s_cselect_b64 s[8:9], -1, 0
	s_cmpk_gt_i32 s2, 0xfff
	s_cbranch_scc1 .LBB0_332
	s_waitcnt lgkmcnt(0)
	s_add_u32 s2, s0, 0x6788000
	s_addc_u32 s18, s1, 0
	s_add_u32 s19, s0, 0x4080000
	s_addc_u32 s20, s1, 0
	v_readlane_b32 s3, v248, 0
	s_cmpk_eq_i32 s3, 0x200
	v_readlane_b32 s24, v248, 3
	s_cselect_b64 s[4:5], -1, 0
	s_lshl_b32 s3, s24, 9
	v_mbcnt_hi_u32_b32 v148, -1, v211
	s_and_b32 s21, s3, 0xe00
	s_lshr_b32 s3, s24, 3
	v_and_b32_e32 v0, 64, v148
	s_add_i32 s21, s21, s3
	v_mov_b32_e32 v129, 0
	s_mov_b64 s[6:7], 0x800
	s_movk_i32 s22, 0x210
	s_mov_b64 s[10:11], 0x40a0000
	s_mov_b64 s[12:13], 0x40a0800
	v_xor_b32_e32 v149, 16, v148
	v_add_u32_e32 v150, 64, v0
	v_xor_b32_e32 v151, 32, v148
	s_mov_b32 s23, 0xf149f2ca
	s_branch .LBB0_325

; __device__ __forceinline__ void run_phase(int ph, KParams kp, unsigned char* smem) {
;     ...
;     case 4: case 7: case 9: case 12: case 15: case 17: {
;       const bf16_t* A; int lda, K; const bf16_t* Bt;
;       if (ph == 4) { A = Z; lda = ZW; K = 768; Bt = (const bf16_t*)(ws + WS_WT_OUT_AB); }
;       else if (ph == 12) { A = Z; lda = ZW; K = 1024; Bt = (const bf16_t*)(ws + WS_WT_OUT_C); }
;       else if (ph == 7 || ph == 15) { A = Z; lda = 1024; K = 1024; Bt = (const bf16_t*)(ws + WS_WT_O) + (size_t)L * 1024 * 1024; }
;       else { A = Z; lda = DFF; K = DFF; Bt = (const bf16_t*)(ws + WS_WT_DOWN) + (size_t)L * 1024 * DFF; }
;       GPre pr; bool pre = false;
;       for (int t = blockIdx.x; t < 512 * 4; t += gridDim.x) {
;         int mt, nt; tile_map(t, 4, gridDim.x, mt, nt);
;         const bool hn = t + (int)gridDim.x < 512 * 4; int mtn = 0, ntn = 0; if (hn) tile_map(t + gridDim.x, 4, gridDim.x, mtn, ntn);
;         EpiResid e{ph == 4 ? xin_row(kp->x_prompt, kp->x_sample, mt * 128) : kp->out + (size_t)mt * 128 * 1024, kp->out};
;         gemm_tile<false>(smem, A + (size_t)mt * 128 * lda, lda, Bt, 1024, K, e, mt * 128, nt * 256, pr, pre, A + (size_t)mtn * 128 * lda, ntn * 256, hn); pre = hn;
;     ...
;     while (__hip_atomic_load(st + 32 * 9, __ATOMIC_RELAXED, __HIP_MEMORY_SCOPE_AGENT) == gen) __builtin_amdgcn_s_sleep(1);
;     __threadfence();
;   }
;   __syncthreads();
.LBB0_342:
	s_sleep 1
	global_load_dword v2, v1, s[6:7] sc1
	s_waitcnt vmcnt(0)
	v_cmp_eq_u32_e32 vcc, v2, v0
	s_cbranch_vccnz .LBB0_342
.LBB0_343:
	buffer_inv sc1
.LBB0_344:
	s_or_b64 exec, exec, s[4:5]
	s_mov_b64 s[6:7], s[26:27]
	s_barrier
	s_load_dwordx2 s[0:1], s[6:7], 0xb0
	v_readlane_b32 s2, v248, 17
	v_readlane_b32 s3, v248, 18
	v_mov_b32_e32 v0, v210
	s_and_b64 vcc, exec, s[2:3]
	s_cbranch_vccnz .LBB0_363
	s_waitcnt lgkmcnt(0)
	s_add_u32 s2, s0, 0x6788000
	s_addc_u32 s33, s1, 0
	s_add_u32 s58, s0, 0x1b80000
	v_readlane_b32 s10, v248, 0
	s_addc_u32 s59, s1, 0
	s_and_b32 s3, s10, 7
	s_cmp_lg_u32 s3, 0
	s_cselect_b64 s[4:5], -1, 0
	s_abs_i32 s60, s10
	v_cvt_f32_u32_e32 v0, s60
	s_ashr_i32 s61, s10, 3
	s_ashr_i32 s62, s10, 31
	s_sub_i32 s3, 0, s60
	v_rcp_iflag_f32_e32 v0, v0
	s_load_dwordx2 s[6:7], s[6:7], 0xa8
	s_mov_b64 s[50:51], 0
	v_mov_b32_e32 v153, 0
	v_mul_f32_e32 v0, 0x4f7ffffe, v0
	v_cvt_u32_f32_e32 v0, v0
	s_mov_b64 s[12:13], 0x20000
	s_mov_b64 s[14:15], 0x1000
	s_mov_b64 s[16:17], 0x2000
	v_readfirstlane_b32 s10, v0
	s_mul_i32 s3, s3, s10
	s_mul_hi_u32 s3, s10, s3
	s_add_i32 s63, s10, s3
	s_add_u32 s64, s0, 0x1ba0000
	s_addc_u32 s65, s1, 0
	s_add_u32 s10, s0, 0x6788080
	s_addc_u32 s11, s1, 0
	s_mov_b64 s[18:19], 0x3000
	s_mov_b64 s[20:21], 0x20040
	s_mov_b64 s[22:23], 0x10000
	s_mov_b64 s[24:25], 0x11000
	s_mov_b64 s[26:27], 0x12000
	s_mov_b64 s[28:29], 0x13000
	s_movk_i32 s66, 0x50
	s_mov_b64 s[30:31], 0x80
	s_mov_b64 s[34:35], 0xc0
	s_mov_b64 s[36:37], 0x100
	s_mov_b64 s[38:39], 0x140
	s_mov_b64 s[40:41], 0x180
	s_mov_b64 s[42:43], 0x1c0
	v_readlane_b32 s47, v248, 3
	s_waitcnt vmcnt(0)
	s_branch .LBB0_347

; __device__ __forceinline__ void run_phase(int ph, KParams kp, unsigned char* smem) {
;     ...
;     case 8: case 16: {
;       const bf16_t* Bt = (const bf16_t*)(ws + WS_WT_GU) + (size_t)L * 5632 * 1024;
;       GPre pr; bool pre = false;
;       for (int t = blockIdx.x; t < 512 * 22; t += gridDim.x) {
;         int mt, nt; tile_map(t, 22, gridDim.x, mt, nt);
;         const bool hn = t + (int)gridDim.x < 512 * 22; int mtn = 0, ntn = 0; if (hn) tile_map(t + gridDim.x, 22, gridDim.x, mtn, ntn);
;         EpiSwiGLU e{Z};
;         gemm_tile<true>(smem, kp->out + (size_t)mt * 128 * 1024, 1024, Bt, 5632, 1024, e, mt * 128, nt * 256, pr, pre, kp->out + (size_t)mtn * 128 * 1024, ntn * 256, hn); pre = hn;
;     ...
;     while (__hip_atomic_load(st + 32 * 9, __ATOMIC_RELAXED, __HIP_MEMORY_SCOPE_AGENT) == gen) __builtin_amdgcn_s_sleep(1);
;     __threadfence();
;   }
;   __syncthreads();
.LBB0_373:
	s_sleep 1
	global_load_dword v2, v1, s[6:7] sc1
	s_waitcnt vmcnt(0)
	v_cmp_eq_u32_e32 vcc, v2, v0
	s_cbranch_vccnz .LBB0_373
.LBB0_374:
	buffer_inv sc1
.LBB0_375:
	s_or_b64 exec, exec, s[4:5]
	s_mov_b64 s[6:7], s[26:27]
	s_barrier
	s_load_dwordx2 s[0:1], s[6:7], 0xb0
	v_readlane_b32 s2, v248, 3
	s_cmpk_lt_i32 s2, 0x2c00
	s_cselect_b64 s[4:5], -1, 0
	v_mov_b32_e32 v0, v210
	v_writelane_b32 v248, s4, 19
	s_cmpk_gt_i32 s2, 0x2bff
	s_nop 0
	v_writelane_b32 v248, s5, 20
	s_cbranch_scc1 .LBB0_403
	s_waitcnt lgkmcnt(0)
	s_add_u32 s4, s0, 0x6788000
	s_addc_u32 s5, s1, 0
	s_add_u32 s2, s0, 0x1f80000
	v_readlane_b32 s14, v248, 0
	s_addc_u32 s33, s1, 0
	s_and_b32 s3, s14, 7
	s_cmp_lg_u32 s3, 0
	s_cselect_b64 s[10:11], -1, 0
	s_abs_i32 s56, s14
	v_cvt_f32_u32_e32 v0, s56
	s_load_dwordx2 s[12:13], s[6:7], 0xa8
	s_sub_i32 s3, 0, s56
	s_ashr_i32 s57, s14, 3
	v_rcp_iflag_f32_e32 v0, v0
	s_ashr_i32 s58, s14, 31
	s_mov_b64 s[52:53], 0
	v_mov_b32_e32 v177, 0
	v_mul_f32_e32 v0, 0x4f7ffffe, v0
	v_cvt_u32_f32_e32 v0, v0
	s_mov_b64 s[16:17], 0x20000
	s_mov_b64 s[18:19], 0x40000
	s_mov_b64 s[20:21], 0x60000
	v_readfirstlane_b32 s6, v0
	s_mul_i32 s3, s3, s6
	s_mul_hi_u32 s3, s6, s3
	s_add_i32 s59, s6, s3
	s_add_u32 s60, s0, 0x2030000
	s_addc_u32 s61, s1, 0
	s_waitcnt lgkmcnt(0)
	s_add_u32 s14, s12, 0x100
	s_addc_u32 s15, s13, 0
	s_mov_b64 s[22:23], 0x1000
	s_mov_b64 s[24:25], 0x2000
	s_mov_b64 s[26:27], 0x3000
	s_mov_b64 s[28:29], 0x80
	s_mov_b64 s[30:31], 0x20080
	s_mov_b64 s[34:35], 0x40080
	s_mov_b64 s[36:37], 0x60080
	s_mov_b64 s[38:39], 0x58000
	s_mov_b64 s[40:41], 0x59000
	s_mov_b64 s[42:43], 0x5a000
	s_mov_b64 s[44:45], 0x5b000
	s_movk_i32 s62, 0x50
	v_mbcnt_hi_u32_b32 v189, -1, v211
	v_mov_b32_e32 v190, 0x358637bd
	s_mov_b32 s63, 0x800000
	s_movk_i32 s64, 0x1600
	v_readlane_b32 s49, v248, 3
	s_waitcnt vmcnt(0)
	s_branch .LBB0_378

; __device__ __forceinline__ void run_phase(int ph, KParams kp, unsigned char* smem) {
;     ...
;     case 4: case 7: case 9: case 12: case 15: case 17: {
;       const bf16_t* A; int lda, K; const bf16_t* Bt;
;       if (ph == 4) { A = Z; lda = ZW; K = 768; Bt = (const bf16_t*)(ws + WS_WT_OUT_AB); }
;       else if (ph == 12) { A = Z; lda = ZW; K = 1024; Bt = (const bf16_t*)(ws + WS_WT_OUT_C); }
;       else if (ph == 7 || ph == 15) { A = Z; lda = 1024; K = 1024; Bt = (const bf16_t*)(ws + WS_WT_O) + (size_t)L * 1024 * 1024; }
;       else { A = Z; lda = DFF; K = DFF; Bt = (const bf16_t*)(ws + WS_WT_DOWN) + (size_t)L * 1024 * DFF; }
;       GPre pr; bool pre = false;
;       for (int t = blockIdx.x; t < 512 * 4; t += gridDim.x) {
;         int mt, nt; tile_map(t, 4, gridDim.x, mt, nt);
;         const bool hn = t + (int)gridDim.x < 512 * 4; int mtn = 0, ntn = 0; if (hn) tile_map(t + gridDim.x, 4, gridDim.x, mtn, ntn);
;         EpiResid e{ph == 4 ? xin_row(kp->x_prompt, kp->x_sample, mt * 128) : kp->out + (size_t)mt * 128 * 1024, kp->out};
;         gemm_tile<false>(smem, A + (size_t)mt * 128 * lda, lda, Bt, 1024, K, e, mt * 128, nt * 256, pr, pre, A + (size_t)mtn * 128 * lda, ntn * 256, hn); pre = hn;
;     ...
;     while (__hip_atomic_load(st + 32 * 9, __ATOMIC_RELAXED, __HIP_MEMORY_SCOPE_AGENT) == gen) __builtin_amdgcn_s_sleep(1);
;     __threadfence();
;   }
;   __syncthreads();
.LBB0_413:
	s_sleep 1
	global_load_dword v2, v1, s[6:7] sc1
	s_waitcnt vmcnt(0)
	v_cmp_eq_u32_e32 vcc, v2, v0
	s_cbranch_vccnz .LBB0_413
.LBB0_414:
	buffer_inv sc1
.LBB0_415:
	s_or_b64 exec, exec, s[4:5]
	s_mov_b64 s[6:7], s[26:27]
	s_barrier
	s_load_dwordx2 s[0:1], s[6:7], 0xb0
	v_readlane_b32 s2, v248, 17
	v_readlane_b32 s3, v248, 18
	v_mov_b32_e32 v0, v210
	s_and_b64 vcc, exec, s[2:3]
	s_cbranch_vccnz .LBB0_434
	s_waitcnt lgkmcnt(0)
	s_add_u32 s2, s0, 0x6788000
	s_addc_u32 s33, s1, 0
	s_add_u32 s56, s0, 0x3580000
	v_readlane_b32 s10, v248, 0
	s_addc_u32 s57, s1, 0
	s_and_b32 s3, s10, 7
	s_cmp_lg_u32 s3, 0
	s_cselect_b64 s[4:5], -1, 0
	s_abs_i32 s58, s10
	v_cvt_f32_u32_e32 v0, s58
	s_ashr_i32 s60, s10, 3
	s_ashr_i32 s61, s10, 31
	s_sub_i32 s3, 0, s58
	v_rcp_iflag_f32_e32 v0, v0
	s_load_dwordx2 s[6:7], s[6:7], 0xa8
	s_mov_b64 s[50:51], 0
	s_movk_i32 s59, 0xb00
	v_mul_f32_e32 v0, 0x4f7ffffe, v0
	v_cvt_u32_f32_e32 v0, v0
	v_mov_b32_e32 v153, 0
	s_mov_b64 s[12:13], 0x58000
	s_mov_b64 s[14:15], 0x1000
	v_readfirstlane_b32 s10, v0
	s_mul_i32 s3, s3, s10
	s_mul_hi_u32 s3, s10, s3
	s_add_i32 s62, s10, s3
	s_add_u32 s63, s0, 0x35a0000
	s_addc_u32 s64, s1, 0
	s_add_u32 s10, s0, 0x6788080
	s_addc_u32 s11, s1, 0
	s_mov_b64 s[16:17], 0x2000
	s_mov_b64 s[18:19], 0x3000
	s_mov_b64 s[20:21], 0x58040
	s_mov_b64 s[22:23], 0x10000
	s_mov_b64 s[24:25], 0x11000
	s_mov_b64 s[26:27], 0x12000
	s_mov_b64 s[28:29], 0x13000
	s_movk_i32 s65, 0x50
	s_movk_i32 s66, 0x1600
	s_mov_b64 s[30:31], 0x80
	s_mov_b64 s[34:35], 0xc0
	s_mov_b64 s[36:37], 0x100
	s_mov_b64 s[38:39], 0x140
	s_mov_b64 s[40:41], 0x180
	s_mov_b64 s[42:43], 0x1c0
	v_readlane_b32 s47, v248, 3
	s_waitcnt vmcnt(0)
	s_branch .LBB0_418

; __device__ __forceinline__ void run_phase(int ph, KParams kp, unsigned char* smem) {
;     ...
;     case 5: case 10: case 13: {
;       const bf16_t* Bt; int NT, ldc;
;       if (ph == 10) { Bt = (const bf16_t*)(ws + WS_WT_IN_C); NT = 12; ldc = ZW; }
;       else { Bt = (const bf16_t*)(ws + WS_WT_Q) + (size_t)L * 1024 * 1024; NT = 4; ldc = 1024; }
;       GPre pr; bool pre = false;
;       for (int t = blockIdx.x; t < 512 * NT; t += gridDim.x) {
;         int mt, nt; tile_map(t, NT, gridDim.x, mt, nt);
;         const bool hn = t + (int)gridDim.x < 512 * NT; int mtn = 0, ntn = 0; if (hn) tile_map(t + gridDim.x, NT, gridDim.x, mtn, ntn);
;         EpiStore<true> e{Z, ldc};
;         gemm_tile<true>(smem, kp->out + (size_t)mt * 128 * 1024, 1024, Bt, NT * 256, 1024, e, mt * 128, nt * 256, pr, pre, kp->out + (size_t)mtn * 128 * 1024, ntn * 256, hn); pre = hn;
;     ...
;     while (__hip_atomic_load(st + 32 * 9, __ATOMIC_RELAXED, __HIP_MEMORY_SCOPE_AGENT) == gen) __builtin_amdgcn_s_sleep(1);
;     __threadfence();
;   }
;   __syncthreads();
.LBB0_444:
	s_sleep 1
	global_load_dword v2, v1, s[6:7] sc1
	s_waitcnt vmcnt(0)
	v_cmp_eq_u32_e32 vcc, v2, v0
	s_cbranch_vccnz .LBB0_444
.LBB0_445:
	buffer_inv sc1
.LBB0_446:
	s_or_b64 exec, exec, s[4:5]
	s_mov_b64 s[6:7], s[26:27]
	s_barrier
	s_load_dwordx2 s[0:1], s[6:7], 0xb0
	v_readlane_b32 s2, v248, 3
	v_mov_b32_e32 v0, v210
	s_cmpk_gt_i32 s2, 0x17ff
	s_cbranch_scc1 .LBB0_474
	s_waitcnt lgkmcnt(0)
	s_add_u32 s4, s0, 0x6788000
	s_addc_u32 s5, s1, 0
	s_add_u32 s2, s0, 0x780000
	v_readlane_b32 s14, v248, 0
	s_addc_u32 s33, s1, 0
	s_and_b32 s3, s14, 7
	s_cmp_lg_u32 s3, 0
	s_cselect_b64 s[10:11], -1, 0
	s_abs_i32 s58, s14
	v_cvt_f32_u32_e32 v0, s58
	s_load_dwordx2 s[12:13], s[6:7], 0xa8
	s_sub_i32 s3, 0, s58
	s_ashr_i32 s60, s14, 3
	v_rcp_iflag_f32_e32 v0, v0
	s_ashr_i32 s61, s14, 31
	s_mov_b64 s[50:51], 0
	s_movk_i32 s59, 0x1800
	v_mul_f32_e32 v0, 0x4f7ffffe, v0
	v_cvt_u32_f32_e32 v0, v0
	v_mov_b32_e32 v177, 0
	s_mov_b64 s[16:17], 0x20000
	s_mov_b64 s[18:19], 0x40000
	v_readfirstlane_b32 s6, v0
	s_mul_i32 s3, s3, s6
	s_mul_hi_u32 s3, s6, s3
	s_add_i32 s62, s6, s3
	s_add_u32 s63, s0, 0x7e0000
	s_addc_u32 s64, s1, 0
	s_waitcnt lgkmcnt(0)
	s_add_u32 s14, s12, 0x100
	s_addc_u32 s15, s13, 0
	s_mov_b64 s[20:21], 0x60000
	s_mov_b64 s[22:23], 0x1000
	s_mov_b64 s[24:25], 0x2000
	s_mov_b64 s[26:27], 0x3000
	s_mov_b64 s[28:29], 0x80
	s_mov_b64 s[30:31], 0x20080
	s_mov_b64 s[34:35], 0x40080
	s_mov_b64 s[36:37], 0x60080
	s_mov_b64 s[38:39], 0x30000
	s_mov_b64 s[40:41], 0x31000
	s_mov_b64 s[42:43], 0x32000
	s_mov_b64 s[44:45], 0x33000
	s_movk_i32 s65, 0x50
	v_mbcnt_hi_u32_b32 v191, -1, v211
	v_mov_b32_e32 v192, 0x358637bd
	s_mov_b32 s66, 0x800000
	v_readlane_b32 s49, v248, 3
	s_waitcnt vmcnt(0)
	s_branch .LBB0_449

; __device__ __forceinline__ void run_phase(int ph, KParams kp, unsigned char* smem) {
;     ...
;     case 11: {
;       float* srpb = (float*)(smem + 2 * 64 * 72 * 2);
;       for (int it = blockIdx.x; it < 4096; it += gridDim.x) {
;         int h = it & 15, t4 = it >> 4;
;         if (gridDim.x == 512) { const int l = (blockIdx.x >> 3) + 64 * (it >> 9); h = 2 * (blockIdx.x & 7) + (l & 1); t4 = l >> 1; }
;         int seqbase, rq, R;
;         if (t4 < 128) { seqbase = (t4 >> 3) * 2048; rq = t4 & 7; R = 32; } else { const int u = t4 - 128; seqbase = NPROMPT + (u >> 6) * 16384; rq = u & 63; R = 256; }
;         const int r0 = 4 * rq;
;         int rb = r0 - 4; rb = rb < 0 ? 0 : rb; rb = rb > R - 8 ? R - 8 : rb;
;         __syncthreads();
;         for (int i = tid; i < 15 * 31; i += 256) srpb[i] = kp->rpb_c[h * 15 * 31 + i];
;         CtxC c{Z + (size_t)seqbase * ZW, srpb, R, r0, rb, h * 64};
;         attn_item<64, 64, 4, true>(smem, c);
;     ...
;     while (__hip_atomic_load(st + 32 * 9, __ATOMIC_RELAXED, __HIP_MEMORY_SCOPE_AGENT) == gen) __builtin_amdgcn_s_sleep(1);
;     __threadfence();
;   }
;   __syncthreads();
.LBB0_484:
	s_sleep 1
	global_load_dword v2, v1, s[6:7] sc1
	s_waitcnt vmcnt(0)
	v_cmp_eq_u32_e32 vcc, v2, v0
	s_cbranch_vccnz .LBB0_484
.LBB0_485:
	buffer_inv sc1
.LBB0_486:
	s_or_b64 exec, exec, s[4:5]
	s_mov_b64 s[0:1], s[26:27]
	s_barrier
	v_cndmask_b32_e64 v0, 0, 1, s[8:9]
	v_writelane_b32 v248, s0, 21
	s_load_dwordx2 s[14:15], s[0:1], 0xb0
	v_mov_b32_e32 v140, v210
	v_writelane_b32 v248, s1, 22
	v_cmp_ne_u32_e64 s[0:1], 1, v0
	s_andn2_b64 vcc, exec, s[8:9]
	s_nop 0
	v_writelane_b32 v248, s0, 23
	s_nop 1
	v_writelane_b32 v248, s1, 24
	s_cbranch_vccnz .LBB0_529
	s_waitcnt lgkmcnt(0)
	s_add_u32 s0, s14, 0x6788000
	v_writelane_b32 v248, s0, 12
	v_writelane_b32 v248, s14, 25
	s_addc_u32 s0, s15, 0
	v_max_i32_e32 v0, 0xd1, v140
	v_writelane_b32 v248, s15, 26
	v_writelane_b32 v248, s0, 14
	v_sub_u32_e32 v0, v0, v140
	v_readlane_b32 s0, v248, 0
	s_cmpk_eq_i32 s0, 0x200
	s_cselect_b64 s[0:1], -1, 0
	v_writelane_b32 v248, s0, 10
	v_add_u32_e32 v0, 0xff, v0
	v_lshrrev_b32_e32 v1, 8, v0
	v_writelane_b32 v248, s1, 11
	v_add_u32_e32 v2, 1, v1
	v_readlane_b32 s2, v248, 3
	s_lshr_b32 s0, s2, 3
	v_writelane_b32 v248, s0, 15
	s_lshl_b32 s0, s2, 1
	s_and_b32 s0, s0, 14
	s_bfe_u32 s1, s2, 0x10003
	s_or_b32 s0, s0, s1
	v_writelane_b32 v248, s0, 16
	s_movk_i32 s0, 0x1d1
	v_cmp_gt_i32_e64 s[0:1], s0, v140
	v_add_u32_e32 v1, -1, v1
	v_lshrrev_b32_e32 v3, 1, v1
	v_writelane_b32 v248, s0, 6
	v_add_u32_e32 v3, 1, v3
	v_and_b32_e32 v158, 7, v3
	v_writelane_b32 v248, s1, 7
	s_movk_i32 s0, 0xff
	v_cmp_lt_u32_e64 s[0:1], s0, v0
	v_and_b32_e32 v0, 0x1fffffe, v2
	v_lshl_add_u32 v153, v0, 8, v140
	v_writelane_b32 v248, s0, 27
	v_lshlrev_b32_e32 v160, 2, v140
	v_add_u32_e32 v141, 0x100, v140
	v_writelane_b32 v248, s1, 28
	v_cmp_lt_u32_e64 s[0:1], 13, v1
	v_and_b32_e32 v159, -8, v3
	s_mov_b32 s15, 0
	v_writelane_b32 v248, s0, 29
	v_add_u32_e32 v161, 0x4800, v160
	v_lshlrev_b32_e32 v162, 2, v153
	v_writelane_b32 v248, s1, 30
	v_cmp_ne_u32_e64 s[0:1], 0, v158
	s_movk_i32 s12, 0x1800
	v_mov_b32_e32 v143, 0
	v_writelane_b32 v248, s0, 31
	s_mov_b64 s[16:17], 0x800
	s_mov_b64 s[4:5], 0x1000
	v_writelane_b32 v248, s1, 32
	v_cmp_ne_u32_e64 s[0:1], v2, v0
	s_mov_b32 s13, 0xf149f2ca
	v_mbcnt_hi_u32_b32 v163, -1, v211
	v_writelane_b32 v248, s0, 33
	v_mov_b32_e32 v164, 0xf149f2ca
	s_nop 0
	v_writelane_b32 v248, s1, 34
	s_mov_b32 s0, s2
	s_branch .LBB0_490

; __device__ __forceinline__ void run_phase(int ph, KParams kp, unsigned char* smem) {
;     ...
;     case 4: case 7: case 9: case 12: case 15: case 17: {
;       const bf16_t* A; int lda, K; const bf16_t* Bt;
;       if (ph == 4) { A = Z; lda = ZW; K = 768; Bt = (const bf16_t*)(ws + WS_WT_OUT_AB); }
;       else if (ph == 12) { A = Z; lda = ZW; K = 1024; Bt = (const bf16_t*)(ws + WS_WT_OUT_C); }
;       else if (ph == 7 || ph == 15) { A = Z; lda = 1024; K = 1024; Bt = (const bf16_t*)(ws + WS_WT_O) + (size_t)L * 1024 * 1024; }
;       else { A = Z; lda = DFF; K = DFF; Bt = (const bf16_t*)(ws + WS_WT_DOWN) + (size_t)L * 1024 * DFF; }
;       GPre pr; bool pre = false;
;       for (int t = blockIdx.x; t < 512 * 4; t += gridDim.x) {
;         int mt, nt; tile_map(t, 4, gridDim.x, mt, nt);
;         const bool hn = t + (int)gridDim.x < 512 * 4; int mtn = 0, ntn = 0; if (hn) tile_map(t + gridDim.x, 4, gridDim.x, mtn, ntn);
;         EpiResid e{ph == 4 ? xin_row(kp->x_prompt, kp->x_sample, mt * 128) : kp->out + (size_t)mt * 128 * 1024, kp->out};
;         gemm_tile<false>(smem, A + (size_t)mt * 128 * lda, lda, Bt, 1024, K, e, mt * 128, nt * 256, pr, pre, A + (size_t)mtn * 128 * lda, ntn * 256, hn); pre = hn;
;     ...
;     while (__hip_atomic_load(st + 32 * 9, __ATOMIC_RELAXED, __HIP_MEMORY_SCOPE_AGENT) == gen) __builtin_amdgcn_s_sleep(1);
;     __threadfence();
;   }
;   __syncthreads();
.LBB0_539:
	s_sleep 1
	global_load_dword v2, v1, s[4:5] sc1
	s_waitcnt vmcnt(0)
	v_cmp_eq_u32_e32 vcc, v2, v0
	s_cbranch_vccnz .LBB0_539
.LBB0_540:
	buffer_inv sc1
.LBB0_541:
	s_or_b64 exec, exec, s[0:1]
	s_mov_b64 s[6:7], s[26:27]
	s_barrier
	s_load_dwordx2 s[0:1], s[6:7], 0xb0
	v_readlane_b32 s2, v248, 17
	v_readlane_b32 s3, v248, 18
	v_mov_b32_e32 v0, v210
	s_and_b64 vcc, exec, s[2:3]
	s_cbranch_vccnz .LBB0_560
	s_waitcnt lgkmcnt(0)
	s_add_u32 s2, s0, 0x6788000
	s_addc_u32 s33, s1, 0
	s_add_u32 s54, s0, 0xd80000
	v_readlane_b32 s8, v248, 0
	s_addc_u32 s55, s1, 0
	s_and_b32 s3, s8, 7
	s_cmp_lg_u32 s3, 0
	s_cselect_b64 s[4:5], -1, 0
	s_abs_i32 s56, s8
	v_cvt_f32_u32_e32 v0, s56
	s_ashr_i32 s58, s8, 3
	s_ashr_i32 s59, s8, 31
	s_sub_i32 s3, 0, s56
	v_rcp_iflag_f32_e32 v0, v0
	s_load_dwordx2 s[6:7], s[6:7], 0xa8
	s_mov_b64 s[48:49], 0
	s_movk_i32 s57, 0xc00
	v_mul_f32_e32 v0, 0x4f7ffffe, v0
	v_cvt_u32_f32_e32 v0, v0
	v_mov_b32_e32 v153, 0
	s_mov_b64 s[10:11], 0x60000
	s_mov_b64 s[12:13], 0x1000
	v_readfirstlane_b32 s8, v0
	s_mul_i32 s3, s3, s8
	s_mul_hi_u32 s3, s8, s3
	s_add_i32 s60, s8, s3
	s_add_u32 s61, s0, 0xda0000
	s_addc_u32 s62, s1, 0
	s_add_u32 s8, s0, 0x6788080
	s_addc_u32 s9, s1, 0
	s_mov_b64 s[14:15], 0x2000
	s_mov_b64 s[16:17], 0x3000
	s_mov_b64 s[18:19], 0x60040
	s_mov_b64 s[20:21], 0x10000
	s_mov_b64 s[22:23], 0x11000
	s_mov_b64 s[24:25], 0x12000
	s_mov_b64 s[26:27], 0x13000
	s_movk_i32 s63, 0x50
	s_movk_i32 s64, 0x1800
	s_mov_b64 s[28:29], 0x80
	s_mov_b64 s[30:31], 0xc0
	s_mov_b64 s[34:35], 0x100
	s_mov_b64 s[36:37], 0x140
	s_mov_b64 s[38:39], 0x180
	s_mov_b64 s[40:41], 0x1c0
	v_readlane_b32 s45, v248, 3
	s_waitcnt vmcnt(0)
	s_branch .LBB0_544

; __device__ __forceinline__ void run_phase(int ph, KParams kp, unsigned char* smem) {
;     ...
;     case 5: case 10: case 13: {
;       const bf16_t* Bt; int NT, ldc;
;       if (ph == 10) { Bt = (const bf16_t*)(ws + WS_WT_IN_C); NT = 12; ldc = ZW; }
;       else { Bt = (const bf16_t*)(ws + WS_WT_Q) + (size_t)L * 1024 * 1024; NT = 4; ldc = 1024; }
;       GPre pr; bool pre = false;
;       for (int t = blockIdx.x; t < 512 * NT; t += gridDim.x) {
;         int mt, nt; tile_map(t, NT, gridDim.x, mt, nt);
;         const bool hn = t + (int)gridDim.x < 512 * NT; int mtn = 0, ntn = 0; if (hn) tile_map(t + gridDim.x, NT, gridDim.x, mtn, ntn);
;         EpiStore<true> e{Z, ldc};
;         gemm_tile<true>(smem, kp->out + (size_t)mt * 128 * 1024, 1024, Bt, NT * 256, 1024, e, mt * 128, nt * 256, pr, pre, kp->out + (size_t)mtn * 128 * 1024, ntn * 256, hn); pre = hn;
;     ...
;     while (__hip_atomic_load(st + 32 * 9, __ATOMIC_RELAXED, __HIP_MEMORY_SCOPE_AGENT) == gen) __builtin_amdgcn_s_sleep(1);
;     __threadfence();
;   }
;   __syncthreads();
.LBB0_570:
	s_sleep 1
	global_load_dword v2, v1, s[6:7] sc1
	s_waitcnt vmcnt(0)
	v_cmp_eq_u32_e32 vcc, v2, v0
	s_cbranch_vccnz .LBB0_570
.LBB0_571:
	buffer_inv sc1
.LBB0_572:
	s_or_b64 exec, exec, s[4:5]
	s_mov_b64 s[6:7], s[26:27]
	s_barrier
	s_load_dwordx2 s[0:1], s[6:7], 0xb0
	v_readlane_b32 s2, v248, 17
	v_readlane_b32 s3, v248, 18
	v_mov_b32_e32 v0, v210
	s_and_b64 vcc, exec, s[2:3]
	s_cbranch_vccnz .LBB0_600
	s_waitcnt lgkmcnt(0)
	s_add_u32 s4, s0, 0x6788000
	s_addc_u32 s5, s1, 0
	s_add_u32 s2, s0, 0x1180000
	v_readlane_b32 s12, v248, 0
	s_addc_u32 s33, s1, 0
	s_and_b32 s3, s12, 7
	s_cmp_lg_u32 s3, 0
	s_cselect_b64 s[8:9], -1, 0
	s_abs_i32 s56, s12
	v_cvt_f32_u32_e32 v0, s56
	s_load_dwordx2 s[10:11], s[6:7], 0xa8
	s_sub_i32 s3, 0, s56
	s_ashr_i32 s57, s12, 3
	v_rcp_iflag_f32_e32 v0, v0
	s_ashr_i32 s58, s12, 31
	s_mov_b64 s[48:49], 0
	v_mov_b32_e32 v177, 0
	v_mul_f32_e32 v0, 0x4f7ffffe, v0
	v_cvt_u32_f32_e32 v0, v0
	s_mov_b64 s[14:15], 0x20000
	s_mov_b64 s[16:17], 0x40000
	s_mov_b64 s[18:19], 0x60000
	v_readfirstlane_b32 s6, v0
	s_mul_i32 s3, s3, s6
	s_mul_hi_u32 s3, s6, s3
	s_add_i32 s59, s6, s3
	s_add_u32 s60, s0, 0x11a0000
	s_addc_u32 s61, s1, 0
	s_waitcnt lgkmcnt(0)
	s_add_u32 s12, s10, 0x100
	s_addc_u32 s13, s11, 0
	s_mov_b64 s[20:21], 0x1000
	s_mov_b64 s[22:23], 0x2000
	s_mov_b64 s[24:25], 0x3000
	s_mov_b64 s[26:27], 0x80
	s_mov_b64 s[28:29], 0x20080
	s_mov_b64 s[30:31], 0x40080
	s_mov_b64 s[34:35], 0x60080
	s_mov_b64 s[36:37], 0x10000
	s_mov_b64 s[38:39], 0x11000
	s_mov_b64 s[40:41], 0x12000
	s_mov_b64 s[42:43], 0x13000
	s_movk_i32 s62, 0x50
	v_mbcnt_hi_u32_b32 v191, -1, v211
	v_mov_b32_e32 v192, 0x358637bd
	s_mov_b32 s63, 0x800000
	v_readlane_b32 s47, v248, 3
	s_waitcnt vmcnt(0)
	s_branch .LBB0_575

; __device__ __forceinline__ void run_phase(int ph, KParams kp, unsigned char* smem) {
;     ...
;     case 6: case 14: {
;       const bf16_t* kvm = (const bf16_t*)(ws + WS_KVMEM) + (size_t)L * 4608 * 2048;
;       for (int it = blockIdx.x; it < 4096; it += gridDim.x) {
;         int idx = it; if (gridDim.x == 512) idx = (blockIdx.x & 7) * 512 + (blockIdx.x >> 3) + 64 * (it >> 9);
;         const int h = idx & 3, tile = idx >> 2, T0 = tile * 64;
;         const int bidx = T0 < NPROMPT ? (T0 >> 11) : 16 + ((T0 - NPROMPT) >> 14);
;         CtxX c{Z + (size_t)T0 * 1024 + h * 256, kvm + (size_t)bidx * 256 * 2048 + h * 256};
;     ...
;     while (__hip_atomic_load(st + 32 * 9, __ATOMIC_RELAXED, __HIP_MEMORY_SCOPE_AGENT) == gen) __builtin_amdgcn_s_sleep(1);
;     __threadfence();
;   }
;   __syncthreads();
.LBB0_610:
	s_sleep 1
	global_load_dword v2, v1, s[6:7] sc1
	s_waitcnt vmcnt(0)
	v_cmp_eq_u32_e32 vcc, v2, v0
	s_cbranch_vccnz .LBB0_610
.LBB0_611:
	buffer_inv sc1
.LBB0_612:
	s_or_b64 exec, exec, s[4:5]
	s_mov_b64 s[0:1], s[26:27]
	s_barrier
	s_load_dwordx2 s[0:1], s[0:1], 0xb0
	v_readlane_b32 s2, v248, 23
	v_readlane_b32 s3, v248, 24
	v_mov_b32_e32 v0, v210
	s_and_b64 vcc, exec, s[2:3]
	s_cbranch_vccnz .LBB0_621
	s_waitcnt lgkmcnt(0)
	s_add_u32 s2, s0, 0x6788000
	s_addc_u32 s16, s1, 0
	s_add_u32 s17, s0, 0x5280000
	s_addc_u32 s18, s1, 0
	v_readlane_b32 s3, v248, 0
	s_cmpk_eq_i32 s3, 0x200
	v_readlane_b32 s22, v248, 3
	s_cselect_b64 s[4:5], -1, 0
	s_lshl_b32 s3, s22, 9
	v_mbcnt_hi_u32_b32 v148, -1, v211
	s_and_b32 s19, s3, 0xe00
	s_lshr_b32 s3, s22, 3
	v_and_b32_e32 v0, 64, v148
	s_add_i32 s19, s19, s3
	v_mov_b32_e32 v129, 0
	s_mov_b64 s[6:7], 0x800
	s_movk_i32 s20, 0x210
	s_mov_b64 s[8:9], 0x52a0000
	s_mov_b64 s[10:11], 0x52a0800
	v_xor_b32_e32 v149, 16, v148
	v_add_u32_e32 v150, 64, v0
	v_xor_b32_e32 v151, 32, v148
	s_mov_b32 s21, 0xf149f2ca
	s_branch .LBB0_615

; __device__ __forceinline__ void run_phase(int ph, KParams kp, unsigned char* smem) {
;     ...
;     case 4: case 7: case 9: case 12: case 15: case 17: {
;       const bf16_t* A; int lda, K; const bf16_t* Bt;
;       if (ph == 4) { A = Z; lda = ZW; K = 768; Bt = (const bf16_t*)(ws + WS_WT_OUT_AB); }
;       else if (ph == 12) { A = Z; lda = ZW; K = 1024; Bt = (const bf16_t*)(ws + WS_WT_OUT_C); }
;       else if (ph == 7 || ph == 15) { A = Z; lda = 1024; K = 1024; Bt = (const bf16_t*)(ws + WS_WT_O) + (size_t)L * 1024 * 1024; }
;       else { A = Z; lda = DFF; K = DFF; Bt = (const bf16_t*)(ws + WS_WT_DOWN) + (size_t)L * 1024 * DFF; }
;       GPre pr; bool pre = false;
;       for (int t = blockIdx.x; t < 512 * 4; t += gridDim.x) {
;         int mt, nt; tile_map(t, 4, gridDim.x, mt, nt);
;         const bool hn = t + (int)gridDim.x < 512 * 4; int mtn = 0, ntn = 0; if (hn) tile_map(t + gridDim.x, 4, gridDim.x, mtn, ntn);
;         EpiResid e{ph == 4 ? xin_row(kp->x_prompt, kp->x_sample, mt * 128) : kp->out + (size_t)mt * 128 * 1024, kp->out};
;         gemm_tile<false>(smem, A + (size_t)mt * 128 * lda, lda, Bt, 1024, K, e, mt * 128, nt * 256, pr, pre, A + (size_t)mtn * 128 * lda, ntn * 256, hn); pre = hn;
;     ...
;     while (__hip_atomic_load(st + 32 * 9, __ATOMIC_RELAXED, __HIP_MEMORY_SCOPE_AGENT) == gen) __builtin_amdgcn_s_sleep(1);
;     __threadfence();
;   }
;   __syncthreads();
.LBB0_631:
	s_sleep 1
	global_load_dword v2, v1, s[6:7] sc1
	s_waitcnt vmcnt(0)
	v_cmp_eq_u32_e32 vcc, v2, v0
	s_cbranch_vccnz .LBB0_631
.LBB0_632:
	buffer_inv sc1
.LBB0_633:
	s_or_b64 exec, exec, s[4:5]
	s_mov_b64 s[6:7], s[26:27]
	s_barrier
	s_load_dwordx2 s[0:1], s[6:7], 0xb0
	v_readlane_b32 s2, v248, 17
	v_readlane_b32 s3, v248, 18
	v_mov_b32_e32 v0, v210
	s_and_b64 vcc, exec, s[2:3]
	s_cbranch_vccnz .LBB0_652
	s_waitcnt lgkmcnt(0)
	s_add_u32 s2, s0, 0x6788000
	s_addc_u32 s33, s1, 0
	s_add_u32 s56, s0, 0x1d80000
	v_readlane_b32 s8, v248, 0
	s_addc_u32 s57, s1, 0
	s_and_b32 s3, s8, 7
	s_cmp_lg_u32 s3, 0
	s_cselect_b64 s[4:5], -1, 0
	s_abs_i32 s58, s8
	v_cvt_f32_u32_e32 v0, s58
	s_ashr_i32 s59, s8, 3
	s_ashr_i32 s60, s8, 31
	s_sub_i32 s3, 0, s58
	v_rcp_iflag_f32_e32 v0, v0
	s_load_dwordx2 s[6:7], s[6:7], 0xa8
	s_mov_b64 s[48:49], 0
	v_mov_b32_e32 v153, 0
	v_mul_f32_e32 v0, 0x4f7ffffe, v0
	v_cvt_u32_f32_e32 v0, v0
	s_mov_b64 s[10:11], 0x20000
	s_mov_b64 s[12:13], 0x1000
	s_mov_b64 s[14:15], 0x2000
	v_readfirstlane_b32 s8, v0
	s_mul_i32 s3, s3, s8
	s_mul_hi_u32 s3, s8, s3
	s_add_i32 s61, s8, s3
	s_add_u32 s62, s0, 0x1da0000
	s_addc_u32 s63, s1, 0
	s_add_u32 s8, s0, 0x6788080
	s_addc_u32 s9, s1, 0
	s_mov_b64 s[16:17], 0x3000
	s_mov_b64 s[18:19], 0x20040
	s_mov_b64 s[20:21], 0x10000
	s_mov_b64 s[22:23], 0x11000
	s_mov_b64 s[24:25], 0x12000
	s_mov_b64 s[26:27], 0x13000
	s_movk_i32 s64, 0x50
	s_mov_b64 s[28:29], 0x80
	s_mov_b64 s[30:31], 0xc0
	s_mov_b64 s[34:35], 0x100
	s_mov_b64 s[36:37], 0x140
	s_mov_b64 s[38:39], 0x180
	s_mov_b64 s[40:41], 0x1c0
	v_readlane_b32 s45, v248, 3
	s_waitcnt vmcnt(0)
	s_branch .LBB0_636

; __device__ __forceinline__ void run_phase(int ph, KParams kp, unsigned char* smem) {
;     ...
;     case 8: case 16: {
;       const bf16_t* Bt = (const bf16_t*)(ws + WS_WT_GU) + (size_t)L * 5632 * 1024;
;       GPre pr; bool pre = false;
;       for (int t = blockIdx.x; t < 512 * 22; t += gridDim.x) {
;         int mt, nt; tile_map(t, 22, gridDim.x, mt, nt);
;         const bool hn = t + (int)gridDim.x < 512 * 22; int mtn = 0, ntn = 0; if (hn) tile_map(t + gridDim.x, 22, gridDim.x, mtn, ntn);
;         EpiSwiGLU e{Z};
;         gemm_tile<true>(smem, kp->out + (size_t)mt * 128 * 1024, 1024, Bt, 5632, 1024, e, mt * 128, nt * 256, pr, pre, kp->out + (size_t)mtn * 128 * 1024, ntn * 256, hn); pre = hn;
;     ...
;     while (__hip_atomic_load(st + 32 * 9, __ATOMIC_RELAXED, __HIP_MEMORY_SCOPE_AGENT) == gen) __builtin_amdgcn_s_sleep(1);
;     __threadfence();
;   }
;   __syncthreads();
.LBB0_662:
	s_sleep 1
	global_load_dword v2, v1, s[6:7] sc1
	s_waitcnt vmcnt(0)
	v_cmp_eq_u32_e32 vcc, v2, v0
	s_cbranch_vccnz .LBB0_662
.LBB0_663:
	buffer_inv sc1
.LBB0_664:
	s_or_b64 exec, exec, s[4:5]
	s_mov_b64 s[6:7], s[26:27]
	s_barrier
	s_load_dwordx2 s[0:1], s[6:7], 0xb0
	v_readlane_b32 s2, v248, 19
	v_readlane_b32 s3, v248, 20
	v_mov_b32_e32 v0, v210
	s_andn2_b64 vcc, exec, s[2:3]
	s_cbranch_vccnz .LBB0_692
	s_waitcnt lgkmcnt(0)
	s_add_u32 s4, s0, 0x6788000
	s_addc_u32 s5, s1, 0
	s_add_u32 s2, s0, 0x2a80000
	v_readlane_b32 s12, v248, 0
	s_addc_u32 s33, s1, 0
	s_and_b32 s3, s12, 7
	s_cmp_lg_u32 s3, 0
	s_cselect_b64 s[8:9], -1, 0
	s_abs_i32 s54, s12
	v_cvt_f32_u32_e32 v0, s54
	s_load_dwordx2 s[10:11], s[6:7], 0xa8
	s_sub_i32 s3, 0, s54
	s_ashr_i32 s55, s12, 3
	v_rcp_iflag_f32_e32 v0, v0
	s_ashr_i32 s56, s12, 31
	s_mov_b64 s[50:51], 0
	v_mov_b32_e32 v177, 0
	v_mul_f32_e32 v0, 0x4f7ffffe, v0
	v_cvt_u32_f32_e32 v0, v0
	s_mov_b64 s[14:15], 0x20000
	s_mov_b64 s[16:17], 0x40000
	s_mov_b64 s[18:19], 0x60000
	v_readfirstlane_b32 s6, v0
	s_mul_i32 s3, s3, s6
	s_mul_hi_u32 s3, s6, s3
	s_add_i32 s57, s6, s3
	s_add_u32 s58, s0, 0x2b30000
	s_addc_u32 s59, s1, 0
	s_waitcnt lgkmcnt(0)
	s_add_u32 s12, s10, 0x100
	s_addc_u32 s13, s11, 0
	s_mov_b64 s[20:21], 0x1000
	s_mov_b64 s[22:23], 0x2000
	s_mov_b64 s[24:25], 0x3000
	s_mov_b64 s[26:27], 0x80
	s_mov_b64 s[28:29], 0x20080
	s_mov_b64 s[30:31], 0x40080
	s_mov_b64 s[34:35], 0x60080
	s_mov_b64 s[36:37], 0x58000
	s_mov_b64 s[38:39], 0x59000
	s_mov_b64 s[40:41], 0x5a000
	s_mov_b64 s[42:43], 0x5b000
	s_movk_i32 s60, 0x50
	v_mbcnt_hi_u32_b32 v189, -1, v211
	v_mov_b32_e32 v190, 0x358637bd
	s_mov_b32 s61, 0x800000
	s_movk_i32 s62, 0x1600
	v_readlane_b32 s47, v248, 3
	s_waitcnt vmcnt(0)
	s_branch .LBB0_667

; __device__ __forceinline__ void run_phase(int ph, KParams kp, unsigned char* smem) {
;     ...
;     case 4: case 7: case 9: case 12: case 15: case 17: {
;       const bf16_t* A; int lda, K; const bf16_t* Bt;
;       if (ph == 4) { A = Z; lda = ZW; K = 768; Bt = (const bf16_t*)(ws + WS_WT_OUT_AB); }
;       else if (ph == 12) { A = Z; lda = ZW; K = 1024; Bt = (const bf16_t*)(ws + WS_WT_OUT_C); }
;       else if (ph == 7 || ph == 15) { A = Z; lda = 1024; K = 1024; Bt = (const bf16_t*)(ws + WS_WT_O) + (size_t)L * 1024 * 1024; }
;       else { A = Z; lda = DFF; K = DFF; Bt = (const bf16_t*)(ws + WS_WT_DOWN) + (size_t)L * 1024 * DFF; }
;       GPre pr; bool pre = false;
;       for (int t = blockIdx.x; t < 512 * 4; t += gridDim.x) {
;         int mt, nt; tile_map(t, 4, gridDim.x, mt, nt);
;         const bool hn = t + (int)gridDim.x < 512 * 4; int mtn = 0, ntn = 0; if (hn) tile_map(t + gridDim.x, 4, gridDim.x, mtn, ntn);
;         EpiResid e{ph == 4 ? xin_row(kp->x_prompt, kp->x_sample, mt * 128) : kp->out + (size_t)mt * 128 * 1024, kp->out};
;         gemm_tile<false>(smem, A + (size_t)mt * 128 * lda, lda, Bt, 1024, K, e, mt * 128, nt * 256, pr, pre, A + (size_t)mtn * 128 * lda, ntn * 256, hn); pre = hn;
;     ...
;     while (__hip_atomic_load(st + 32 * 9, __ATOMIC_RELAXED, __HIP_MEMORY_SCOPE_AGENT) == gen) __builtin_amdgcn_s_sleep(1);
;     __threadfence();
;   }
;   __syncthreads();
.LBB0_702:
	s_sleep 1
	global_load_dword v2, v1, s[6:7] sc1
	s_waitcnt vmcnt(0)
	v_cmp_eq_u32_e32 vcc, v2, v0
	s_cbranch_vccnz .LBB0_702
.LBB0_703:
	buffer_inv sc1
.LBB0_704:
	s_or_b64 exec, exec, s[4:5]
	s_mov_b64 s[6:7], s[26:27]
	s_barrier
	s_load_dwordx2 s[0:1], s[6:7], 0xb0
	v_readlane_b32 s2, v248, 17
	v_readlane_b32 s3, v248, 18
	v_mov_b32_e32 v0, v210
	s_and_b64 vcc, exec, s[2:3]
	s_cbranch_vccnz .LBB0_723
	s_waitcnt lgkmcnt(0)
	s_add_u32 s2, s0, 0x6788000
	s_addc_u32 s33, s1, 0
	s_add_u32 s54, s0, 0x3b00000
	v_readlane_b32 s8, v248, 0
	s_addc_u32 s55, s1, 0
	s_and_b32 s3, s8, 7
	s_cmp_lg_u32 s3, 0
	s_cselect_b64 s[4:5], -1, 0
	s_abs_i32 s56, s8
	v_cvt_f32_u32_e32 v0, s56
	s_ashr_i32 s58, s8, 3
	s_ashr_i32 s59, s8, 31
	s_sub_i32 s3, 0, s56
	v_rcp_iflag_f32_e32 v0, v0
	s_load_dwordx2 s[6:7], s[6:7], 0xa8
	s_mov_b64 s[48:49], 0
	s_movk_i32 s57, 0xb00
	v_mul_f32_e32 v0, 0x4f7ffffe, v0
	v_cvt_u32_f32_e32 v0, v0
	v_mov_b32_e32 v153, 0
	s_mov_b64 s[10:11], 0x58000
	s_mov_b64 s[12:13], 0x1000
	v_readfirstlane_b32 s8, v0
	s_mul_i32 s3, s3, s8
	s_mul_hi_u32 s3, s8, s3
	s_add_i32 s60, s8, s3
	s_add_u32 s61, s0, 0x3b20000
	s_addc_u32 s62, s1, 0
	s_add_u32 s8, s0, 0x6788080
	s_addc_u32 s9, s1, 0
	s_mov_b64 s[14:15], 0x2000
	s_mov_b64 s[16:17], 0x3000
	s_mov_b64 s[18:19], 0x58040
	s_mov_b64 s[20:21], 0x10000
	s_mov_b64 s[22:23], 0x11000
	s_mov_b64 s[24:25], 0x12000
	s_mov_b64 s[26:27], 0x13000
	s_movk_i32 s63, 0x50
	s_movk_i32 s64, 0x1600
	s_mov_b64 s[28:29], 0x80
	s_mov_b64 s[30:31], 0xc0
	s_mov_b64 s[34:35], 0x100
	s_mov_b64 s[36:37], 0x140
	s_mov_b64 s[38:39], 0x180
	s_mov_b64 s[40:41], 0x1c0
	v_readlane_b32 s45, v248, 3
	s_waitcnt vmcnt(0)
	s_branch .LBB0_707

; __device__ __forceinline__ void run_phase(int ph, KParams kp, unsigned char* smem) {
;     ...
;       const int lane = tid & 63, wv = blockIdx.x * 4 + (tid >> 6), nwv = gridDim.x * 4;
;       for (int row = wv; row < NTOK; row += nwv) {
;         float* xr = kp->out + (size_t)row * 1024;
;         f32x4 v[4]; float s = 0.f;
; #pragma unroll
;         for (int i = 0; i < 4; ++i) { v[i] = ld_agent_f32x4(xr + i * 256 + lane * 4); s += v[i][0] * v[i][0] + v[i][1] * v[i][1] + v[i][2] * v[i][2] + v[i][3] * v[i][3]; }
;         s += __shfl_xor(s, 1); s += __shfl_xor(s, 2); s += __shfl_xor(s, 4); s += __shfl_xor(s, 8); s += __shfl_xor(s, 16); s += __shfl_xor(s, 32);
;         const float r = rsqrtf(s * (1.0f / 1024.0f) + EPS);
; #pragma unroll
;         for (int i = 0; i < 4; ++i) { const f32x4 g = *(const f32x4*)(kp->g_final + i * 256 + lane * 4); *(f32x4*)(xr + i * 256 + lane * 4) = v[i] * r * g; }
;       }
;     ...
;     while (__hip_atomic_load(st + 32 * 9, __ATOMIC_RELAXED, __HIP_MEMORY_SCOPE_AGENT) == gen) __builtin_amdgcn_s_sleep(1);
;     __threadfence();
.LBB0_733:
	s_sleep 1
	global_load_dword v2, v1, s[6:7] sc1
	s_waitcnt vmcnt(0)
	v_cmp_eq_u32_e32 vcc, v2, v0
	s_cbranch_vccnz .LBB0_733
.LBB0_734:
	buffer_inv sc1
.LBB0_735:
	s_or_b64 exec, exec, s[4:5]
	s_barrier
	v_readlane_b32 s0, v248, 3
	v_ashrrev_i32_e32 v0, 6, v210
	s_nop 0
	v_lshl_add_u32 v0, s0, 2, v0
	s_mov_b32 s0, 0x10000
	v_cmp_gt_i32_e32 vcc, s0, v0
	s_and_saveexec_b64 s[0:1], vcc
	s_cbranch_execz .LBB0_738
	v_mbcnt_hi_u32_b32 v1, -1, v211
	v_and_b32_e32 v3, 64, v1
	v_xor_b32_e32 v2, 1, v1
	v_add_u32_e32 v3, 64, v3
	v_cmp_lt_i32_e32 vcc, v2, v3
	s_load_dwordx4 s[4:7], s[26:27], 0xa0
	v_readlane_b32 s0, v248, 0
	v_cndmask_b32_e32 v2, v1, v2, vcc
	v_lshlrev_b32_e32 v6, 2, v2
	v_xor_b32_e32 v2, 2, v1
	v_cmp_lt_i32_e32 vcc, v2, v3
	s_lshl_b32 s0, s0, 2
	s_ashr_i32 s1, s0, 31
	v_cndmask_b32_e32 v2, v1, v2, vcc
	v_lshlrev_b32_e32 v7, 2, v2
	v_xor_b32_e32 v2, 4, v1
	v_cmp_lt_i32_e32 vcc, v2, v3
	s_lshl_b64 s[2:3], s[0:1], 12
	s_mov_b32 s1, 0x800000
	v_cndmask_b32_e32 v2, v1, v2, vcc
	v_lshlrev_b32_e32 v8, 2, v2
	v_xor_b32_e32 v2, 8, v1
	v_cmp_lt_i32_e32 vcc, v2, v3
	s_nop 1
	v_cndmask_b32_e32 v2, v1, v2, vcc
	v_lshlrev_b32_e32 v9, 2, v2
	v_xor_b32_e32 v2, 16, v1
	v_cmp_lt_i32_e32 vcc, v2, v3
	s_nop 1
	v_cndmask_b32_e32 v2, v1, v2, vcc
	v_lshlrev_b32_e32 v10, 2, v2
	v_xor_b32_e32 v2, 32, v1
	v_cmp_lt_i32_e32 vcc, v2, v3
	v_mov_b32_e32 v3, 0
	s_nop 0
	v_cndmask_b32_e32 v1, v1, v2, vcc
	v_lshlrev_b32_e32 v11, 2, v1
	v_lshlrev_b32_e32 v1, 4, v210
	v_and_b32_e32 v2, 0x3f0, v1
	v_ashrrev_i32_e32 v1, 31, v0
	v_lshlrev_b64 v[4:5], 12, v[0:1]
	v_and_b32_e32 v1, 63, v210
	v_lshl_or_b32 v4, v1, 4, v4
	s_waitcnt lgkmcnt(0)
	v_lshl_add_u64 v[2:3], s[4:5], 0, v[2:3]
	v_lshl_add_u64 v[4:5], s[6:7], 0, v[4:5]
	s_mov_b64 s[4:5], 0
	v_mov_b32_e32 v1, 0x358637bd
	s_mov_b32 s6, 0xffff
.LBB0_737:
	global_load_dwordx4 v[40:43], v[2:3], off
	global_load_dwordx4 v[44:47], v[2:3], off offset:1024
	global_load_dwordx4 v[48:51], v[2:3], off offset:2048
	global_load_dwordx4 v[52:55], v[2:3], off offset:3072
	global_load_dwordx4 v[16:19], v[4:5], off sc1
	global_load_dwordx4 v[20:23], v[4:5], off offset:1024 sc1
	global_load_dwordx4 v[24:27], v[4:5], off offset:2048 sc1
	global_load_dwordx4 v[28:31], v[4:5], off offset:3072 sc1
	v_readfirstlane_b32 s12, v0
	s_waitcnt vmcnt(0)
.Lfn_loop:
	s_add_i32 s12, s12, s0
	v_lshl_add_u64 v[58:59], v[4:5], 0, s[2:3]
	s_cmp_lt_i32 s12, 0x10000
	s_cselect_b32 s13, 1, 0
	s_cbranch_scc0 .Lfn_compute
	global_load_dwordx4 v[60:63], v[58:59], off sc1
	global_load_dwordx4 v[64:67], v[58:59], off offset:1024 sc1
	global_load_dwordx4 v[68:71], v[58:59], off offset:2048 sc1
	global_load_dwordx4 v[72:75], v[58:59], off offset:3072 sc1
.Lfn_compute:
	v_mul_f32_e32 v34, v17, v17
	v_fmac_f32_e32 v34, v16, v16
	v_mul_f32_e32 v35, v21, v21
	v_fmac_f32_e32 v35, v20, v20
	v_mul_f32_e32 v36, v25, v25
	v_fmac_f32_e32 v36, v24, v24
	v_pk_mul_f32 v[32:33], v[28:29], v[28:29]
	v_fmac_f32_e32 v34, v18, v18
	v_fmac_f32_e32 v35, v22, v22
	v_add_f32_e32 v32, v32, v33
	v_fmac_f32_e32 v36, v26, v26
	v_fmac_f32_e32 v34, v19, v19
	v_fmac_f32_e32 v35, v23, v23
	v_fmac_f32_e32 v32, v30, v30
	v_fmac_f32_e32 v36, v27, v27
	v_add_f32_e32 v33, v34, v35
	v_fmac_f32_e32 v32, v31, v31
	v_add_f32_e32 v33, v33, v36
	v_add_f32_e32 v32, v33, v32
	ds_bpermute_b32 v33, v6, v32
	s_waitcnt lgkmcnt(0)
	v_add_f32_e32 v32, v32, v33
	ds_bpermute_b32 v33, v7, v32
	s_waitcnt lgkmcnt(0)
	v_add_f32_e32 v32, v32, v33
	ds_bpermute_b32 v33, v8, v32
	s_waitcnt lgkmcnt(0)
	v_add_f32_e32 v32, v32, v33
	ds_bpermute_b32 v33, v9, v32
	s_waitcnt lgkmcnt(0)
	v_add_f32_e32 v32, v32, v33
	ds_bpermute_b32 v33, v10, v32
	s_waitcnt lgkmcnt(0)
	v_add_f32_e32 v32, v32, v33
	ds_bpermute_b32 v33, v11, v32
	s_waitcnt lgkmcnt(0)
	v_add_f32_e32 v32, v32, v33
	v_fmamk_f32 v32, v32, 0x3a800000, v1
	v_mul_f32_e32 v33, 0x4b800000, v32
	v_cmp_gt_f32_e32 vcc, s1, v32
	s_nop 1
	v_cndmask_b32_e32 v32, v32, v33, vcc
	v_rsq_f32_e32 v32, v32
	s_nop 0
	v_mul_f32_e32 v33, 0x45800000, v32
	v_cndmask_b32_e32 v32, v32, v33, vcc
	v_pk_mul_f32 v[16:17], v[16:17], v[32:33] op_sel_hi:[1,0]
	v_pk_mul_f32 v[18:19], v[18:19], v[32:33] op_sel_hi:[1,0]
	v_pk_mul_f32 v[20:21], v[20:21], v[32:33] op_sel_hi:[1,0]
	v_pk_mul_f32 v[22:23], v[22:23], v[32:33] op_sel_hi:[1,0]
	v_pk_mul_f32 v[24:25], v[24:25], v[32:33] op_sel_hi:[1,0]
	v_pk_mul_f32 v[26:27], v[26:27], v[32:33] op_sel_hi:[1,0]
	v_pk_mul_f32 v[28:29], v[28:29], v[32:33] op_sel_hi:[1,0]
	v_pk_mul_f32 v[30:31], v[30:31], v[32:33] op_sel_hi:[1,0]
	v_pk_mul_f32 v[16:17], v[40:41], v[16:17]
	v_pk_mul_f32 v[18:19], v[42:43], v[18:19]
	v_pk_mul_f32 v[20:21], v[44:45], v[20:21]
	v_pk_mul_f32 v[22:23], v[46:47], v[22:23]
	v_pk_mul_f32 v[24:25], v[48:49], v[24:25]
	v_pk_mul_f32 v[26:27], v[50:51], v[26:27]
	v_pk_mul_f32 v[28:29], v[52:53], v[28:29]
	v_pk_mul_f32 v[30:31], v[54:55], v[30:31]
	global_store_dwordx4 v[4:5], v[16:19], off
	global_store_dwordx4 v[4:5], v[20:23], off offset:1024
	global_store_dwordx4 v[4:5], v[24:27], off offset:2048
	global_store_dwordx4 v[4:5], v[28:31], off offset:3072
	s_cmp_eq_u32 s13, 0
	s_cbranch_scc1 .LBB0_738
	s_waitcnt vmcnt(4)
	s_nop 1
	v_mov_b32_e32 v16, v60
	v_mov_b32_e32 v17, v61
	v_mov_b32_e32 v18, v62
	v_mov_b32_e32 v19, v63
	v_mov_b32_e32 v20, v64
	v_mov_b32_e32 v21, v65
	v_mov_b32_e32 v22, v66
	v_mov_b32_e32 v23, v67
	v_mov_b32_e32 v24, v68
	v_mov_b32_e32 v25, v69
	v_mov_b32_e32 v26, v70
	v_mov_b32_e32 v27, v71
	v_mov_b32_e32 v28, v72
	v_mov_b32_e32 v29, v73
	v_mov_b32_e32 v30, v74
	v_mov_b32_e32 v31, v75
	v_mov_b32_e32 v4, v58
	v_mov_b32_e32 v5, v59
	s_branch .Lfn_loop
